# stack + xcd-barrier leaders poll the top arrival counter + GLA stage-0 gate loop as two interleaved token streams
# speedup vs baseline: 1.0203x; 1.0064x over previous
; __device__ __forceinline__ unsigned xb_ld(unsigned* p)              { return __hip_atomic_load(p, __ATOMIC_RELAXED, __HIP_MEMORY_SCOPE_AGENT); }
; __device__ __forceinline__ unsigned xb_add(unsigned* p, unsigned v) { return __hip_atomic_fetch_add(p, v, __ATOMIC_RELAXED, __HIP_MEMORY_SCOPE_AGENT); }
; #define XB_SPIN(cond, bar) do { unsigned _sp = 0; while (cond) { __builtin_amdgcn_s_sleep(1); \
;     if ((++_sp & 255u) == 0u) { if (xb_ld(&(bar)[XB_TMO])) break; if (_sp > XB_SPIN_CAP) { atomicAdd(&(bar)[XB_TMO], 1u); break; } } } } while (0)
; __device__ __forceinline__ void xcd_barrier(const XcdBarrier& b) {
;     ...
;         if (old + 1u == (gen + 1u) * nloc) {
;             __builtin_amdgcn_fence(__ATOMIC_RELEASE, "agent");
;             asm volatile("s_waitcnt vmcnt(0)" ::: "memory");
;             const unsigned og = xb_add(&bar[XB_TOP], 1u);
;             const unsigned tg = og / nx;
;             if (og + 1u == (tg + 1u) * nx) xb_add(&bar[XB_TOPGEN], 1u);
;             else XB_SPIN(xb_ld(&bar[XB_TOPGEN]) == tg, bar);
;             __builtin_amdgcn_fence(__ATOMIC_ACQUIRE, "agent");
.LBB0_90:
	s_or_b64 exec, exec, s[14:15]
	v_cvt_f32_u32_e32 v3, v0
	s_waitcnt vmcnt(0)
	v_readfirstlane_b32 s6, v2
	s_add_u32 s14, s62, 0xc3500
	s_addc_u32 s15, s63, 0
	v_rcp_iflag_f32_e32 v3, v3
	v_add_u32_e32 v1, s6, v1
	v_add_u32_e32 v4, 1, v1
	s_mov_b64 s[16:17], -1
	v_mul_f32_e32 v2, 0x4f7ffffe, v3
	v_cvt_u32_f32_e32 v2, v2
	v_sub_u32_e32 v3, 0, v0
	v_mul_lo_u32 v3, v3, v2
	v_mul_hi_u32 v3, v2, v3
	v_add_u32_e32 v2, v2, v3
	v_mul_hi_u32 v2, v1, v2
	v_mul_lo_u32 v3, v2, v0
	v_sub_u32_e32 v1, v1, v3
	v_add_u32_e32 v5, 1, v2
	v_cmp_ge_u32_e32 vcc, v1, v0
	v_sub_u32_e32 v3, v1, v0
	s_nop 0
	v_cndmask_b32_e32 v2, v2, v5, vcc
	v_cndmask_b32_e32 v1, v1, v3, vcc
	v_add_u32_e32 v3, 1, v2
	v_cmp_ge_u32_e32 vcc, v1, v0
	s_nop 1
	v_cndmask_b32_e32 v2, v2, v3, vcc
	v_mul_lo_u32 v1, v0, v2
	v_add_u32_e32 v0, v1, v0
	v_mov_b32_e32 v5, v0
	v_cmp_ne_u32_e32 vcc, v4, v0
	v_mov_b64_e32 v[0:1], s[14:15]
	s_and_saveexec_b64 s[12:13], vcc
	s_cbranch_execz .LBB0_102
	v_mov_b32_e32 v0, 0
	global_load_dword v1, v0, s[14:15] offset:-256 sc1
	s_mov_b64 s[24:25], 0
	s_waitcnt vmcnt(0)
	v_cmp_lt_u32_e32 vcc, v1, v5
	s_and_saveexec_b64 s[18:19], vcc
	s_cbranch_execz .LBB0_101
	s_add_u32 s16, s62, 0xc0200
	s_addc_u32 s17, s63, 0
	s_mov_b32 s6, 1
	s_branch .LBB0_94

; __device__ __forceinline__ unsigned xb_ld(unsigned* p)              { return __hip_atomic_load(p, __ATOMIC_RELAXED, __HIP_MEMORY_SCOPE_AGENT); }
; #define XB_SPIN(cond, bar) do { unsigned _sp = 0; while (cond) { __builtin_amdgcn_s_sleep(1); \
;     if ((++_sp & 255u) == 0u) { if (xb_ld(&(bar)[XB_TMO])) break; if (_sp > XB_SPIN_CAP) { atomicAdd(&(bar)[XB_TMO], 1u); break; } } } } while (0)
; __device__ __forceinline__ void xcd_barrier(const XcdBarrier& b) {
;     ...
;             else XB_SPIN(xb_ld(&bar[XB_TOPGEN]) == tg, bar);
.LBB0_96:
	global_load_dword v1, v0, s[14:15] offset:-256 sc1
	s_add_i32 s6, s6, 1
	s_mov_b64 s[26:27], -1
	s_waitcnt vmcnt(0)
	v_cmp_ge_u32_e32 vcc, v1, v5
	s_orn2_b64 s[72:73], vcc, exec
	s_branch .LBB0_93

; __device__ __forceinline__ unsigned xb_ld(unsigned* p)              { return __hip_atomic_load(p, __ATOMIC_RELAXED, __HIP_MEMORY_SCOPE_AGENT); }
; __device__ __forceinline__ unsigned xb_add(unsigned* p, unsigned v) { return __hip_atomic_fetch_add(p, v, __ATOMIC_RELAXED, __HIP_MEMORY_SCOPE_AGENT); }
; #define XB_SPIN(cond, bar) do { unsigned _sp = 0; while (cond) { __builtin_amdgcn_s_sleep(1); \
;     if ((++_sp & 255u) == 0u) { if (xb_ld(&(bar)[XB_TMO])) break; if (_sp > XB_SPIN_CAP) { atomicAdd(&(bar)[XB_TMO], 1u); break; } } } } while (0)
; __device__ __forceinline__ void xcd_barrier(const XcdBarrier& b) {
;     ...
;         if (old + 1u == (gen + 1u) * nloc) {
;             __builtin_amdgcn_fence(__ATOMIC_RELEASE, "agent");
;             asm volatile("s_waitcnt vmcnt(0)" ::: "memory");
;             const unsigned og = xb_add(&bar[XB_TOP], 1u);
;             const unsigned tg = og / nx;
;             if (og + 1u == (tg + 1u) * nx) xb_add(&bar[XB_TOPGEN], 1u);
;             else XB_SPIN(xb_ld(&bar[XB_TOPGEN]) == tg, bar);
;             __builtin_amdgcn_fence(__ATOMIC_ACQUIRE, "agent");
.LBB0_170:
	s_or_b64 exec, exec, s[12:13]
	v_cvt_f32_u32_e32 v3, v0
	s_waitcnt vmcnt(0)
	v_readfirstlane_b32 s6, v2
	s_add_u32 s12, s62, 0xc3500
	s_addc_u32 s13, s63, 0
	v_rcp_iflag_f32_e32 v3, v3
	v_add_u32_e32 v1, s6, v1
	v_add_u32_e32 v4, 1, v1
	s_mov_b64 s[14:15], -1
	v_mul_f32_e32 v2, 0x4f7ffffe, v3
	v_cvt_u32_f32_e32 v2, v2
	v_sub_u32_e32 v3, 0, v0
	v_mul_lo_u32 v3, v3, v2
	v_mul_hi_u32 v3, v2, v3
	v_add_u32_e32 v2, v2, v3
	v_mul_hi_u32 v2, v1, v2
	v_mul_lo_u32 v3, v2, v0
	v_sub_u32_e32 v1, v1, v3
	v_add_u32_e32 v5, 1, v2
	v_cmp_ge_u32_e32 vcc, v1, v0
	v_sub_u32_e32 v3, v1, v0
	s_nop 0
	v_cndmask_b32_e32 v2, v2, v5, vcc
	v_cndmask_b32_e32 v1, v1, v3, vcc
	v_add_u32_e32 v3, 1, v2
	v_cmp_ge_u32_e32 vcc, v1, v0
	s_nop 1
	v_cndmask_b32_e32 v2, v2, v3, vcc
	v_mul_lo_u32 v1, v0, v2
	v_add_u32_e32 v0, v1, v0
	v_mov_b32_e32 v5, v0
	v_cmp_ne_u32_e32 vcc, v4, v0
	v_mov_b64_e32 v[0:1], s[12:13]
	s_and_saveexec_b64 s[8:9], vcc
	s_cbranch_execz .LBB0_182
	v_mov_b32_e32 v0, 0
	global_load_dword v1, v0, s[12:13] offset:-256 sc1
	s_mov_b64 s[18:19], 0
	s_waitcnt vmcnt(0)
	v_cmp_lt_u32_e32 vcc, v1, v5
	s_and_saveexec_b64 s[16:17], vcc
	s_cbranch_execz .LBB0_181
	s_add_u32 s14, s62, 0xc0200
	s_addc_u32 s15, s63, 0
	s_mov_b32 s6, 1
	s_branch .LBB0_174

; __device__ __forceinline__ unsigned xb_ld(unsigned* p)              { return __hip_atomic_load(p, __ATOMIC_RELAXED, __HIP_MEMORY_SCOPE_AGENT); }
; #define XB_SPIN(cond, bar) do { unsigned _sp = 0; while (cond) { __builtin_amdgcn_s_sleep(1); \
;     if ((++_sp & 255u) == 0u) { if (xb_ld(&(bar)[XB_TMO])) break; if (_sp > XB_SPIN_CAP) { atomicAdd(&(bar)[XB_TMO], 1u); break; } } } } while (0)
; __device__ __forceinline__ void xcd_barrier(const XcdBarrier& b) {
;     ...
;             else XB_SPIN(xb_ld(&bar[XB_TOPGEN]) == tg, bar);
.LBB0_176:
	global_load_dword v1, v0, s[12:13] offset:-256 sc1
	s_add_i32 s6, s6, 1
	s_mov_b64 s[26:27], -1
	s_waitcnt vmcnt(0)
	v_cmp_ge_u32_e32 vcc, v1, v5
	s_orn2_b64 s[50:51], vcc, exec
	s_branch .LBB0_173

; __device__ __forceinline__ unsigned xb_ld(unsigned* p)              { return __hip_atomic_load(p, __ATOMIC_RELAXED, __HIP_MEMORY_SCOPE_AGENT); }
; __device__ __forceinline__ unsigned xb_add(unsigned* p, unsigned v) { return __hip_atomic_fetch_add(p, v, __ATOMIC_RELAXED, __HIP_MEMORY_SCOPE_AGENT); }
; #define XB_SPIN(cond, bar) do { unsigned _sp = 0; while (cond) { __builtin_amdgcn_s_sleep(1); \
;     if ((++_sp & 255u) == 0u) { if (xb_ld(&(bar)[XB_TMO])) break; if (_sp > XB_SPIN_CAP) { atomicAdd(&(bar)[XB_TMO], 1u); break; } } } } while (0)
; __device__ __forceinline__ void xcd_barrier(const XcdBarrier& b) {
;     ...
;         if (old + 1u == (gen + 1u) * nloc) {
;             __builtin_amdgcn_fence(__ATOMIC_RELEASE, "agent");
;             asm volatile("s_waitcnt vmcnt(0)" ::: "memory");
;             const unsigned og = xb_add(&bar[XB_TOP], 1u);
;             const unsigned tg = og / nx;
;             if (og + 1u == (tg + 1u) * nx) xb_add(&bar[XB_TOPGEN], 1u);
;             else XB_SPIN(xb_ld(&bar[XB_TOPGEN]) == tg, bar);
;             __builtin_amdgcn_fence(__ATOMIC_ACQUIRE, "agent");
.LBB0_242:
	s_or_b64 exec, exec, s[12:13]
	v_cvt_f32_u32_e32 v3, v0
	s_waitcnt vmcnt(0)
	v_readfirstlane_b32 s6, v2
	s_add_u32 s12, s62, 0xc3500
	s_addc_u32 s13, s63, 0
	v_rcp_iflag_f32_e32 v3, v3
	v_add_u32_e32 v1, s6, v1
	v_add_u32_e32 v4, 1, v1
	s_mov_b64 s[14:15], -1
	v_mul_f32_e32 v2, 0x4f7ffffe, v3
	v_cvt_u32_f32_e32 v2, v2
	v_sub_u32_e32 v3, 0, v0
	v_mul_lo_u32 v3, v3, v2
	v_mul_hi_u32 v3, v2, v3
	v_add_u32_e32 v2, v2, v3
	v_mul_hi_u32 v2, v1, v2
	v_mul_lo_u32 v3, v2, v0
	v_sub_u32_e32 v1, v1, v3
	v_add_u32_e32 v5, 1, v2
	v_cmp_ge_u32_e32 vcc, v1, v0
	v_sub_u32_e32 v3, v1, v0
	s_nop 0
	v_cndmask_b32_e32 v2, v2, v5, vcc
	v_cndmask_b32_e32 v1, v1, v3, vcc
	v_add_u32_e32 v3, 1, v2
	v_cmp_ge_u32_e32 vcc, v1, v0
	s_nop 1
	v_cndmask_b32_e32 v2, v2, v3, vcc
	v_mul_lo_u32 v1, v0, v2
	v_add_u32_e32 v0, v1, v0
	v_mov_b32_e32 v5, v0
	v_cmp_ne_u32_e32 vcc, v4, v0
	v_mov_b64_e32 v[0:1], s[12:13]
	s_and_saveexec_b64 s[6:7], vcc
	s_cbranch_execz .LBB0_254
	v_mov_b32_e32 v0, 0
	global_load_dword v1, v0, s[12:13] offset:-256 sc1
	s_mov_b64 s[18:19], 0
	s_waitcnt vmcnt(0)
	v_cmp_lt_u32_e32 vcc, v1, v5
	s_and_saveexec_b64 s[16:17], vcc
	s_cbranch_execz .LBB0_253
	s_add_u32 s14, s62, 0xc0200
	s_addc_u32 s15, s63, 0
	s_mov_b32 s8, 1
	s_branch .LBB0_246

; __device__ __forceinline__ unsigned xb_ld(unsigned* p)              { return __hip_atomic_load(p, __ATOMIC_RELAXED, __HIP_MEMORY_SCOPE_AGENT); }
; #define XB_SPIN(cond, bar) do { unsigned _sp = 0; while (cond) { __builtin_amdgcn_s_sleep(1); \
;     if ((++_sp & 255u) == 0u) { if (xb_ld(&(bar)[XB_TMO])) break; if (_sp > XB_SPIN_CAP) { atomicAdd(&(bar)[XB_TMO], 1u); break; } } } } while (0)
; __device__ __forceinline__ void xcd_barrier(const XcdBarrier& b) {
;     ...
;             else XB_SPIN(xb_ld(&bar[XB_TOPGEN]) == tg, bar);
.LBB0_248:
	global_load_dword v1, v0, s[12:13] offset:-256 sc1
	s_add_i32 s8, s8, 1
	s_mov_b64 s[22:23], -1
	s_waitcnt vmcnt(0)
	v_cmp_ge_u32_e32 vcc, v1, v5
	s_orn2_b64 s[26:27], vcc, exec
	s_branch .LBB0_245

; __device__ __forceinline__ unsigned xb_ld(unsigned* p)              { return __hip_atomic_load(p, __ATOMIC_RELAXED, __HIP_MEMORY_SCOPE_AGENT); }
; __device__ __forceinline__ unsigned xb_add(unsigned* p, unsigned v) { return __hip_atomic_fetch_add(p, v, __ATOMIC_RELAXED, __HIP_MEMORY_SCOPE_AGENT); }
; #define XB_SPIN(cond, bar) do { unsigned _sp = 0; while (cond) { __builtin_amdgcn_s_sleep(1); \
;     if ((++_sp & 255u) == 0u) { if (xb_ld(&(bar)[XB_TMO])) break; if (_sp > XB_SPIN_CAP) { atomicAdd(&(bar)[XB_TMO], 1u); break; } } } } while (0)
; __device__ __forceinline__ void xcd_barrier(const XcdBarrier& b) {
;     ...
;         if (old + 1u == (gen + 1u) * nloc) {
;             __builtin_amdgcn_fence(__ATOMIC_RELEASE, "agent");
;             asm volatile("s_waitcnt vmcnt(0)" ::: "memory");
;             const unsigned og = xb_add(&bar[XB_TOP], 1u);
;             const unsigned tg = og / nx;
;             if (og + 1u == (tg + 1u) * nx) xb_add(&bar[XB_TOPGEN], 1u);
;             else XB_SPIN(xb_ld(&bar[XB_TOPGEN]) == tg, bar);
;             __builtin_amdgcn_fence(__ATOMIC_ACQUIRE, "agent");
.LBB0_441:
	s_or_b64 exec, exec, s[10:11]
	v_cvt_f32_u32_e32 v3, v0
	s_waitcnt vmcnt(0)
	v_readfirstlane_b32 s6, v2
	s_add_u32 s10, s62, 0xc3500
	s_addc_u32 s11, s63, 0
	v_rcp_iflag_f32_e32 v3, v3
	v_add_u32_e32 v1, s6, v1
	v_add_u32_e32 v4, 1, v1
	s_mov_b64 s[12:13], -1
	v_mul_f32_e32 v2, 0x4f7ffffe, v3
	v_cvt_u32_f32_e32 v2, v2
	v_sub_u32_e32 v3, 0, v0
	v_mul_lo_u32 v3, v3, v2
	v_mul_hi_u32 v3, v2, v3
	v_add_u32_e32 v2, v2, v3
	v_mul_hi_u32 v2, v1, v2
	v_mul_lo_u32 v3, v2, v0
	v_sub_u32_e32 v1, v1, v3
	v_add_u32_e32 v5, 1, v2
	v_cmp_ge_u32_e32 vcc, v1, v0
	v_sub_u32_e32 v3, v1, v0
	s_nop 0
	v_cndmask_b32_e32 v2, v2, v5, vcc
	v_cndmask_b32_e32 v1, v1, v3, vcc
	v_add_u32_e32 v3, 1, v2
	v_cmp_ge_u32_e32 vcc, v1, v0
	s_nop 1
	v_cndmask_b32_e32 v2, v2, v3, vcc
	v_mul_lo_u32 v1, v0, v2
	v_add_u32_e32 v0, v1, v0
	v_mov_b32_e32 v5, v0
	v_cmp_ne_u32_e32 vcc, v4, v0
	v_mov_b64_e32 v[0:1], s[10:11]
	s_and_saveexec_b64 s[6:7], vcc
	s_cbranch_execz .LBB0_453
	v_mov_b32_e32 v0, 0
	global_load_dword v1, v0, s[10:11] offset:-256 sc1
	s_mov_b64 s[16:17], 0
	s_waitcnt vmcnt(0)
	v_cmp_lt_u32_e32 vcc, v1, v5
	s_and_saveexec_b64 s[14:15], vcc
	s_cbranch_execz .LBB0_452
	s_add_u32 s12, s62, 0xc0200
	s_addc_u32 s13, s63, 0
	s_mov_b32 s8, 1
	s_branch .LBB0_445

; __device__ __forceinline__ unsigned xb_ld(unsigned* p)              { return __hip_atomic_load(p, __ATOMIC_RELAXED, __HIP_MEMORY_SCOPE_AGENT); }
; #define XB_SPIN(cond, bar) do { unsigned _sp = 0; while (cond) { __builtin_amdgcn_s_sleep(1); \
;     if ((++_sp & 255u) == 0u) { if (xb_ld(&(bar)[XB_TMO])) break; if (_sp > XB_SPIN_CAP) { atomicAdd(&(bar)[XB_TMO], 1u); break; } } } } while (0)
; __device__ __forceinline__ void xcd_barrier(const XcdBarrier& b) {
;     ...
;             else XB_SPIN(xb_ld(&bar[XB_TOPGEN]) == tg, bar);
.LBB0_447:
	global_load_dword v1, v0, s[10:11] offset:-256 sc1
	s_add_i32 s8, s8, 1
	s_mov_b64 s[20:21], -1
	s_waitcnt vmcnt(0)
	v_cmp_ge_u32_e32 vcc, v1, v5
	s_orn2_b64 s[24:25], vcc, exec
	s_branch .LBB0_444

; #define LAS __attribute__((address_space(3)))
; template <int MODE>
; __device__ __forceinline__ void gla_item(const Frame& F, int hh, int grp, const bf16_t* BB, const float* BZ, const float* w2g, const float* biasg, const float* gn, bf16_t* SLOC, float* DG, bf16_t* Hout) {
;     ...
;             for (int ii = 0; ii < 16; ++ii) {
;                 const LAS float* bz = (const LAS float*)(L + GL_BZ) + (16 * qr + ii) * 16;
;                 float z = bias;
; #pragma unroll
;                 for (int r = 0; r < 16; ++r) z += bz[r] * w2r[r];
;                 const float ls = -__logf(1.0f + __expf(-fmaxf(z, -80.f)));
;                 run += ls * (1.0f / 16.0f); csl[(16 * qr + ii) * 128 + dd] = run;
;             }
;             ((LAS float*)(L + GL_TOT))[qr * 128 + dd] = run;
;             __syncthreads();
;             float pre = 0.f;
; #pragma unroll
;             for (int qq = 0; qq < 4; ++qq) { const float tv = ((const LAS float*)(L + GL_TOT))[qq * 128 + dd]; total += tv; if (qq < qr) pre += tv; }
.LBB0_466:
	v_add_u32_e32 v67, 0x17c00, v65
	ds_read_b128 v[68:71], v67
	ds_read_b128 v[72:75], v67 offset:16
	ds_read_b128 v[76:79], v67 offset:32
	ds_read_b128 v[154:157], v67 offset:48
	ds_read_b128 v[240:243], v67 offset:64
	ds_read_b128 v[244:247], v67 offset:80
	ds_read_b128 v[248:251], v67 offset:96
	ds_read_b128 v[184:187], v67 offset:112
	v_add_u32_e32 v158, 0x19e00, v66
	v_add_u32_e32 v159, 0x1a000, v66
	s_add_i32 s12, s12, -2
	v_add_u32_e32 v66, 0x400, v66
	v_add_u32_e32 v65, 0x80, v65
	s_waitcnt lgkmcnt(0)
	v_fma_f32 v182, v126, v68, v147
	v_fma_f32 v190, v126, v240, v147
	v_mul_f32_e32 v183, v130, v72
	v_mul_f32_e32 v191, v130, v244
	v_mul_f32_e32 v188, v145, v76
	v_mul_f32_e32 v192, v145, v248
	v_mul_f32_e32 v189, v92, v154
	v_mul_f32_e32 v193, v92, v184
	v_fmac_f32_e32 v182, v127, v69
	v_fmac_f32_e32 v190, v127, v241
	v_fmac_f32_e32 v183, v131, v73
	v_fmac_f32_e32 v191, v131, v245
	v_fmac_f32_e32 v188, v146, v77
	v_fmac_f32_e32 v192, v146, v249
	v_fmac_f32_e32 v189, v93, v155
	v_fmac_f32_e32 v193, v93, v185
	v_fmac_f32_e32 v182, v128, v70
	v_fmac_f32_e32 v190, v128, v242
	v_fmac_f32_e32 v183, v135, v74
	v_fmac_f32_e32 v191, v135, v246
	v_fmac_f32_e32 v188, v90, v78
	v_fmac_f32_e32 v192, v90, v250
	v_fmac_f32_e32 v189, v94, v156
	v_fmac_f32_e32 v193, v94, v186
	v_fmac_f32_e32 v182, v129, v71
	v_fmac_f32_e32 v190, v129, v243
	v_fmac_f32_e32 v183, v144, v75
	v_fmac_f32_e32 v191, v144, v247
	v_fmac_f32_e32 v188, v91, v79
	v_fmac_f32_e32 v192, v91, v251
	v_fmac_f32_e32 v189, v95, v157
	v_fmac_f32_e32 v193, v95, v187
	v_add_f32_e32 v182, v182, v183
	v_add_f32_e32 v190, v190, v191
	v_add_f32_e32 v188, v188, v189
	v_add_f32_e32 v192, v192, v193
	v_add_f32_e32 v182, v182, v188
	v_add_f32_e32 v190, v190, v192
	v_max_f32_e32 v182, 0xc2a00000, v182
	v_max_f32_e32 v190, 0xc2a00000, v190
	v_mul_f32_e32 v182, 0xbfb8aa3b, v182
	v_mul_f32_e32 v190, 0xbfb8aa3b, v190
	v_exp_f32_e32 v182, v182
	v_exp_f32_e32 v190, v190
	v_add_f32_e32 v182, 1.0, v182
	v_add_f32_e32 v190, 1.0, v190
	v_log_f32_e32 v182, v182
	v_log_f32_e32 v190, v190
	v_mul_f32_e32 v194, 0x3f317217, v182
	v_mul_f32_e32 v196, 0x3f317217, v190
	v_fma_f32 v194, v182, s50, -v194
	v_fma_f32 v196, v190, s50, -v196
	v_fmac_f32_e32 v194, 0x3377d1cf, v182
	v_fmac_f32_e32 v196, 0x3377d1cf, v190
	v_fmac_f32_e32 v194, 0x3f317217, v182
	v_fmac_f32_e32 v196, 0x3f317217, v190
	v_fmac_f32_e32 v64, 0xbd800000, v194
	s_cmp_eq_u32 s12, 0
	ds_write_b32 v158, v64
	v_fmac_f32_e32 v64, 0xbd800000, v196
	s_nop 0
	ds_write_b32 v159, v64
	s_cbranch_scc0 .LBB0_466
	ds_write_b32 v107, v64
	s_waitcnt lgkmcnt(0)
	s_barrier
	ds_read2st64_b32 v[64:65], v108 offset1:2
	ds_read2st64_b32 v[66:67], v108 offset0:4 offset1:6
	s_mov_b64 s[22:23], 0
	s_waitcnt lgkmcnt(1)
	v_add_f32_e32 v64, 0, v64
	v_cndmask_b32_e64 v68, v64, 0, s[4:5]
	v_add_f32_e32 v64, v64, v65
	v_add_f32_e32 v65, v65, v68
	v_cndmask_b32_e64 v65, v68, v65, s[6:7]
	s_waitcnt lgkmcnt(0)
	v_add_f32_e32 v64, v64, v66
	v_add_f32_e32 v66, v66, v65
	v_cndmask_b32_e64 v65, v65, v66, s[8:9]
	v_add_f32_e32 v66, v67, v65
	v_add_f32_e32 v64, v64, v67
	v_cndmask_b32_e64 v65, v65, v66, s[10:11]
	v_mov_b32_e32 v66, v114
	v_mov_b32_e32 v67, v116

; __device__ __forceinline__ unsigned xb_ld(unsigned* p)              { return __hip_atomic_load(p, __ATOMIC_RELAXED, __HIP_MEMORY_SCOPE_AGENT); }
; __device__ __forceinline__ unsigned xb_add(unsigned* p, unsigned v) { return __hip_atomic_fetch_add(p, v, __ATOMIC_RELAXED, __HIP_MEMORY_SCOPE_AGENT); }
; #define XB_SPIN(cond, bar) do { unsigned _sp = 0; while (cond) { __builtin_amdgcn_s_sleep(1); \
;     if ((++_sp & 255u) == 0u) { if (xb_ld(&(bar)[XB_TMO])) break; if (_sp > XB_SPIN_CAP) { atomicAdd(&(bar)[XB_TMO], 1u); break; } } } } while (0)
; __device__ __forceinline__ void xcd_barrier(const XcdBarrier& b) {
;     ...
;         if (old + 1u == (gen + 1u) * nloc) {
;             __builtin_amdgcn_fence(__ATOMIC_RELEASE, "agent");
;             asm volatile("s_waitcnt vmcnt(0)" ::: "memory");
;             const unsigned og = xb_add(&bar[XB_TOP], 1u);
;             const unsigned tg = og / nx;
;             if (og + 1u == (tg + 1u) * nx) xb_add(&bar[XB_TOPGEN], 1u);
;             else XB_SPIN(xb_ld(&bar[XB_TOPGEN]) == tg, bar);
;             __builtin_amdgcn_fence(__ATOMIC_ACQUIRE, "agent");
.LBB0_521:
	s_or_b64 exec, exec, s[8:9]
	v_cvt_f32_u32_e32 v3, v0
	s_waitcnt vmcnt(0)
	v_readfirstlane_b32 s6, v2
	s_add_u32 s8, s62, 0xc3500
	s_addc_u32 s9, s63, 0
	v_rcp_iflag_f32_e32 v3, v3
	v_add_u32_e32 v1, s6, v1
	v_add_u32_e32 v4, 1, v1
	s_mov_b64 s[10:11], -1
	v_mul_f32_e32 v2, 0x4f7ffffe, v3
	v_cvt_u32_f32_e32 v2, v2
	v_sub_u32_e32 v3, 0, v0
	v_mul_lo_u32 v3, v3, v2
	v_mul_hi_u32 v3, v2, v3
	v_add_u32_e32 v2, v2, v3
	v_mul_hi_u32 v2, v1, v2
	v_mul_lo_u32 v3, v2, v0
	v_sub_u32_e32 v1, v1, v3
	v_add_u32_e32 v5, 1, v2
	v_cmp_ge_u32_e32 vcc, v1, v0
	v_sub_u32_e32 v3, v1, v0
	s_nop 0
	v_cndmask_b32_e32 v2, v2, v5, vcc
	v_cndmask_b32_e32 v1, v1, v3, vcc
	v_add_u32_e32 v3, 1, v2
	v_cmp_ge_u32_e32 vcc, v1, v0
	s_nop 1
	v_cndmask_b32_e32 v2, v2, v3, vcc
	v_mul_lo_u32 v1, v0, v2
	v_add_u32_e32 v0, v1, v0
	v_mov_b32_e32 v5, v0
	v_cmp_ne_u32_e32 vcc, v4, v0
	v_mov_b64_e32 v[0:1], s[8:9]
	s_and_saveexec_b64 s[6:7], vcc
	s_cbranch_execz .LBB0_533
	v_mov_b32_e32 v0, 0
	global_load_dword v1, v0, s[8:9] offset:-256 sc1
	s_mov_b64 s[14:15], 0
	s_waitcnt vmcnt(0)
	v_cmp_lt_u32_e32 vcc, v1, v5
	s_and_saveexec_b64 s[12:13], vcc
	s_cbranch_execz .LBB0_532
	s_add_u32 s10, s62, 0xc0200
	s_addc_u32 s11, s63, 0
	s_mov_b32 s28, 1
	s_branch .LBB0_525

; __device__ __forceinline__ unsigned xb_ld(unsigned* p)              { return __hip_atomic_load(p, __ATOMIC_RELAXED, __HIP_MEMORY_SCOPE_AGENT); }
; #define XB_SPIN(cond, bar) do { unsigned _sp = 0; while (cond) { __builtin_amdgcn_s_sleep(1); \
;     if ((++_sp & 255u) == 0u) { if (xb_ld(&(bar)[XB_TMO])) break; if (_sp > XB_SPIN_CAP) { atomicAdd(&(bar)[XB_TMO], 1u); break; } } } } while (0)
; __device__ __forceinline__ void xcd_barrier(const XcdBarrier& b) {
;     ...
;             else XB_SPIN(xb_ld(&bar[XB_TOPGEN]) == tg, bar);
.LBB0_527:
	global_load_dword v1, v0, s[8:9] offset:-256 sc1
	s_add_i32 s28, s28, 1
	s_mov_b64 s[22:23], -1
	s_waitcnt vmcnt(0)
	v_cmp_ge_u32_e32 vcc, v1, v5
	s_orn2_b64 s[26:27], vcc, exec
	s_branch .LBB0_524

; __device__ __forceinline__ unsigned xb_ld(unsigned* p)              { return __hip_atomic_load(p, __ATOMIC_RELAXED, __HIP_MEMORY_SCOPE_AGENT); }
; __device__ __forceinline__ unsigned xb_add(unsigned* p, unsigned v) { return __hip_atomic_fetch_add(p, v, __ATOMIC_RELAXED, __HIP_MEMORY_SCOPE_AGENT); }
; #define XB_SPIN(cond, bar) do { unsigned _sp = 0; while (cond) { __builtin_amdgcn_s_sleep(1); \
;     if ((++_sp & 255u) == 0u) { if (xb_ld(&(bar)[XB_TMO])) break; if (_sp > XB_SPIN_CAP) { atomicAdd(&(bar)[XB_TMO], 1u); break; } } } } while (0)
; __device__ __forceinline__ void xcd_barrier(const XcdBarrier& b) {
;     ...
;         if (old + 1u == (gen + 1u) * nloc) {
;             __builtin_amdgcn_fence(__ATOMIC_RELEASE, "agent");
;             asm volatile("s_waitcnt vmcnt(0)" ::: "memory");
;             const unsigned og = xb_add(&bar[XB_TOP], 1u);
;             const unsigned tg = og / nx;
;             if (og + 1u == (tg + 1u) * nx) xb_add(&bar[XB_TOPGEN], 1u);
;             else XB_SPIN(xb_ld(&bar[XB_TOPGEN]) == tg, bar);
;             __builtin_amdgcn_fence(__ATOMIC_ACQUIRE, "agent");
.LBB0_593:
	s_or_b64 exec, exec, s[10:11]
	v_cvt_f32_u32_e32 v3, v0
	s_waitcnt vmcnt(0)
	v_readfirstlane_b32 s8, v2
	s_add_u32 s10, s62, 0xc3500
	s_addc_u32 s11, s63, 0
	v_rcp_iflag_f32_e32 v3, v3
	v_add_u32_e32 v1, s8, v1
	v_add_u32_e32 v4, 1, v1
	s_mov_b64 s[12:13], -1
	v_mul_f32_e32 v2, 0x4f7ffffe, v3
	v_cvt_u32_f32_e32 v2, v2
	v_sub_u32_e32 v3, 0, v0
	v_mul_lo_u32 v3, v3, v2
	v_mul_hi_u32 v3, v2, v3
	v_add_u32_e32 v2, v2, v3
	v_mul_hi_u32 v2, v1, v2
	v_mul_lo_u32 v3, v2, v0
	v_sub_u32_e32 v1, v1, v3
	v_add_u32_e32 v5, 1, v2
	v_cmp_ge_u32_e32 vcc, v1, v0
	v_sub_u32_e32 v3, v1, v0
	s_nop 0
	v_cndmask_b32_e32 v2, v2, v5, vcc
	v_cndmask_b32_e32 v1, v1, v3, vcc
	v_add_u32_e32 v3, 1, v2
	v_cmp_ge_u32_e32 vcc, v1, v0
	s_nop 1
	v_cndmask_b32_e32 v2, v2, v3, vcc
	v_mul_lo_u32 v1, v0, v2
	v_add_u32_e32 v0, v1, v0
	v_mov_b32_e32 v5, v0
	v_cmp_ne_u32_e32 vcc, v4, v0
	v_mov_b64_e32 v[0:1], s[10:11]
	s_and_saveexec_b64 s[8:9], vcc
	s_cbranch_execz .LBB0_605
	v_mov_b32_e32 v0, 0
	global_load_dword v1, v0, s[10:11] offset:-256 sc1
	s_mov_b64 s[16:17], 0
	s_waitcnt vmcnt(0)
	v_cmp_lt_u32_e32 vcc, v1, v5
	s_and_saveexec_b64 s[14:15], vcc
	s_cbranch_execz .LBB0_604
	s_add_u32 s12, s62, 0xc0200
	s_addc_u32 s13, s63, 0
	s_mov_b32 s28, 1
	s_branch .LBB0_597

; __device__ __forceinline__ unsigned xb_ld(unsigned* p)              { return __hip_atomic_load(p, __ATOMIC_RELAXED, __HIP_MEMORY_SCOPE_AGENT); }
; #define XB_SPIN(cond, bar) do { unsigned _sp = 0; while (cond) { __builtin_amdgcn_s_sleep(1); \
;     if ((++_sp & 255u) == 0u) { if (xb_ld(&(bar)[XB_TMO])) break; if (_sp > XB_SPIN_CAP) { atomicAdd(&(bar)[XB_TMO], 1u); break; } } } } while (0)
; __device__ __forceinline__ void xcd_barrier(const XcdBarrier& b) {
;     ...
;             else XB_SPIN(xb_ld(&bar[XB_TOPGEN]) == tg, bar);
.LBB0_599:
	global_load_dword v1, v0, s[10:11] offset:-256 sc1
	s_add_i32 s28, s28, 1
	s_mov_b64 s[22:23], -1
	s_waitcnt vmcnt(0)
	v_cmp_ge_u32_e32 vcc, v1, v5
	s_orn2_b64 s[26:27], vcc, exec
	s_branch .LBB0_596

; __device__ __forceinline__ unsigned xb_ld(unsigned* p)              { return __hip_atomic_load(p, __ATOMIC_RELAXED, __HIP_MEMORY_SCOPE_AGENT); }
; __device__ __forceinline__ unsigned xb_add(unsigned* p, unsigned v) { return __hip_atomic_fetch_add(p, v, __ATOMIC_RELAXED, __HIP_MEMORY_SCOPE_AGENT); }
; #define XB_SPIN(cond, bar) do { unsigned _sp = 0; while (cond) { __builtin_amdgcn_s_sleep(1); \
;     if ((++_sp & 255u) == 0u) { if (xb_ld(&(bar)[XB_TMO])) break; if (_sp > XB_SPIN_CAP) { atomicAdd(&(bar)[XB_TMO], 1u); break; } } } } while (0)
; __device__ __forceinline__ void xcd_barrier(const XcdBarrier& b) {
;     ...
;         if (old + 1u == (gen + 1u) * nloc) {
;             __builtin_amdgcn_fence(__ATOMIC_RELEASE, "agent");
;             asm volatile("s_waitcnt vmcnt(0)" ::: "memory");
;             const unsigned og = xb_add(&bar[XB_TOP], 1u);
;             const unsigned tg = og / nx;
;             if (og + 1u == (tg + 1u) * nx) xb_add(&bar[XB_TOPGEN], 1u);
;             else XB_SPIN(xb_ld(&bar[XB_TOPGEN]) == tg, bar);
;             __builtin_amdgcn_fence(__ATOMIC_ACQUIRE, "agent");
.LBB0_674:
	s_or_b64 exec, exec, s[8:9]
	v_cvt_f32_u32_e32 v3, v0
	s_waitcnt vmcnt(0)
	v_readfirstlane_b32 s6, v2
	s_add_u32 s8, s62, 0xc3500
	s_addc_u32 s9, s63, 0
	v_rcp_iflag_f32_e32 v3, v3
	v_add_u32_e32 v1, s6, v1
	v_add_u32_e32 v4, 1, v1
	s_mov_b64 s[10:11], -1
	v_mul_f32_e32 v2, 0x4f7ffffe, v3
	v_cvt_u32_f32_e32 v2, v2
	v_sub_u32_e32 v3, 0, v0
	v_mul_lo_u32 v3, v3, v2
	v_mul_hi_u32 v3, v2, v3
	v_add_u32_e32 v2, v2, v3
	v_mul_hi_u32 v2, v1, v2
	v_mul_lo_u32 v3, v2, v0
	v_sub_u32_e32 v1, v1, v3
	v_add_u32_e32 v5, 1, v2
	v_cmp_ge_u32_e32 vcc, v1, v0
	v_sub_u32_e32 v3, v1, v0
	s_nop 0
	v_cndmask_b32_e32 v2, v2, v5, vcc
	v_cndmask_b32_e32 v1, v1, v3, vcc
	v_add_u32_e32 v3, 1, v2
	v_cmp_ge_u32_e32 vcc, v1, v0
	s_nop 1
	v_cndmask_b32_e32 v2, v2, v3, vcc
	v_mul_lo_u32 v1, v0, v2
	v_add_u32_e32 v0, v1, v0
	v_mov_b32_e32 v5, v0
	v_cmp_ne_u32_e32 vcc, v4, v0
	v_mov_b64_e32 v[0:1], s[8:9]
	s_and_saveexec_b64 s[6:7], vcc
	s_cbranch_execz .LBB0_686
	v_mov_b32_e32 v0, 0
	global_load_dword v1, v0, s[8:9] offset:-256 sc1
	s_mov_b64 s[14:15], 0
	s_waitcnt vmcnt(0)
	v_cmp_lt_u32_e32 vcc, v1, v5
	s_and_saveexec_b64 s[12:13], vcc
	s_cbranch_execz .LBB0_685
	s_add_u32 s10, s62, 0xc0200
	s_addc_u32 s11, s63, 0
	s_mov_b32 s24, 1
	s_branch .LBB0_678

; __device__ __forceinline__ unsigned xb_ld(unsigned* p)              { return __hip_atomic_load(p, __ATOMIC_RELAXED, __HIP_MEMORY_SCOPE_AGENT); }
; #define XB_SPIN(cond, bar) do { unsigned _sp = 0; while (cond) { __builtin_amdgcn_s_sleep(1); \
;     if ((++_sp & 255u) == 0u) { if (xb_ld(&(bar)[XB_TMO])) break; if (_sp > XB_SPIN_CAP) { atomicAdd(&(bar)[XB_TMO], 1u); break; } } } } while (0)
; __device__ __forceinline__ void xcd_barrier(const XcdBarrier& b) {
;     ...
;             else XB_SPIN(xb_ld(&bar[XB_TOPGEN]) == tg, bar);
.LBB0_680:
	global_load_dword v1, v0, s[8:9] offset:-256 sc1
	s_add_i32 s24, s24, 1
	s_mov_b64 s[18:19], -1
	s_waitcnt vmcnt(0)
	v_cmp_ge_u32_e32 vcc, v1, v5
	s_orn2_b64 s[22:23], vcc, exec
	s_branch .LBB0_677

; __device__ __forceinline__ unsigned xb_ld(unsigned* p)              { return __hip_atomic_load(p, __ATOMIC_RELAXED, __HIP_MEMORY_SCOPE_AGENT); }
; __device__ __forceinline__ unsigned xb_add(unsigned* p, unsigned v) { return __hip_atomic_fetch_add(p, v, __ATOMIC_RELAXED, __HIP_MEMORY_SCOPE_AGENT); }
; #define XB_SPIN(cond, bar) do { unsigned _sp = 0; while (cond) { __builtin_amdgcn_s_sleep(1); \
;     if ((++_sp & 255u) == 0u) { if (xb_ld(&(bar)[XB_TMO])) break; if (_sp > XB_SPIN_CAP) { atomicAdd(&(bar)[XB_TMO], 1u); break; } } } } while (0)
; __device__ __forceinline__ void xcd_barrier(const XcdBarrier& b) {
;     ...
;         if (old + 1u == (gen + 1u) * nloc) {
;             __builtin_amdgcn_fence(__ATOMIC_RELEASE, "agent");
;             asm volatile("s_waitcnt vmcnt(0)" ::: "memory");
;             const unsigned og = xb_add(&bar[XB_TOP], 1u);
;             const unsigned tg = og / nx;
;             if (og + 1u == (tg + 1u) * nx) xb_add(&bar[XB_TOPGEN], 1u);
;             else XB_SPIN(xb_ld(&bar[XB_TOPGEN]) == tg, bar);
;             __builtin_amdgcn_fence(__ATOMIC_ACQUIRE, "agent");
.LBB0_753:
	s_or_b64 exec, exec, s[10:11]
	v_cvt_f32_u32_e32 v3, v0
	s_waitcnt vmcnt(0)
	v_readfirstlane_b32 s8, v2
	s_add_u32 s10, s62, 0xc3500
	s_addc_u32 s11, s63, 0
	v_rcp_iflag_f32_e32 v3, v3
	v_add_u32_e32 v1, s8, v1
	v_add_u32_e32 v4, 1, v1
	s_mov_b64 s[12:13], -1
	v_mul_f32_e32 v2, 0x4f7ffffe, v3
	v_cvt_u32_f32_e32 v2, v2
	v_sub_u32_e32 v3, 0, v0
	v_mul_lo_u32 v3, v3, v2
	v_mul_hi_u32 v3, v2, v3
	v_add_u32_e32 v2, v2, v3
	v_mul_hi_u32 v2, v1, v2
	v_mul_lo_u32 v3, v2, v0
	v_sub_u32_e32 v1, v1, v3
	v_add_u32_e32 v5, 1, v2
	v_cmp_ge_u32_e32 vcc, v1, v0
	v_sub_u32_e32 v3, v1, v0
	s_nop 0
	v_cndmask_b32_e32 v2, v2, v5, vcc
	v_cndmask_b32_e32 v1, v1, v3, vcc
	v_add_u32_e32 v3, 1, v2
	v_cmp_ge_u32_e32 vcc, v1, v0
	s_nop 1
	v_cndmask_b32_e32 v2, v2, v3, vcc
	v_mul_lo_u32 v1, v0, v2
	v_add_u32_e32 v0, v1, v0
	v_mov_b32_e32 v5, v0
	v_cmp_ne_u32_e32 vcc, v4, v0
	v_mov_b64_e32 v[0:1], s[10:11]
	s_and_saveexec_b64 s[8:9], vcc
	s_cbranch_execz .LBB0_765
	v_mov_b32_e32 v0, 0
	global_load_dword v1, v0, s[10:11] offset:-256 sc1
	s_mov_b64 s[16:17], 0
	s_waitcnt vmcnt(0)
	v_cmp_lt_u32_e32 vcc, v1, v5
	s_and_saveexec_b64 s[14:15], vcc
	s_cbranch_execz .LBB0_764
	s_add_u32 s12, s62, 0xc0200
	s_addc_u32 s13, s63, 0
	s_mov_b32 s26, 1
	s_branch .LBB0_757

; __device__ __forceinline__ unsigned xb_ld(unsigned* p)              { return __hip_atomic_load(p, __ATOMIC_RELAXED, __HIP_MEMORY_SCOPE_AGENT); }
; #define XB_SPIN(cond, bar) do { unsigned _sp = 0; while (cond) { __builtin_amdgcn_s_sleep(1); \
;     if ((++_sp & 255u) == 0u) { if (xb_ld(&(bar)[XB_TMO])) break; if (_sp > XB_SPIN_CAP) { atomicAdd(&(bar)[XB_TMO], 1u); break; } } } } while (0)
; __device__ __forceinline__ void xcd_barrier(const XcdBarrier& b) {
;     ...
;             else XB_SPIN(xb_ld(&bar[XB_TOPGEN]) == tg, bar);
.LBB0_759:
	global_load_dword v1, v0, s[10:11] offset:-256 sc1
	s_add_i32 s26, s26, 1
	s_mov_b64 s[20:21], -1
	s_waitcnt vmcnt(0)
	v_cmp_ge_u32_e32 vcc, v1, v5
	s_orn2_b64 s[24:25], vcc, exec
	s_branch .LBB0_756

; __device__ __forceinline__ unsigned xb_ld(unsigned* p)              { return __hip_atomic_load(p, __ATOMIC_RELAXED, __HIP_MEMORY_SCOPE_AGENT); }
; __device__ __forceinline__ unsigned xb_add(unsigned* p, unsigned v) { return __hip_atomic_fetch_add(p, v, __ATOMIC_RELAXED, __HIP_MEMORY_SCOPE_AGENT); }
; #define XB_SPIN(cond, bar) do { unsigned _sp = 0; while (cond) { __builtin_amdgcn_s_sleep(1); \
;     if ((++_sp & 255u) == 0u) { if (xb_ld(&(bar)[XB_TMO])) break; if (_sp > XB_SPIN_CAP) { atomicAdd(&(bar)[XB_TMO], 1u); break; } } } } while (0)
; __device__ __forceinline__ void xcd_barrier(const XcdBarrier& b) {
;     ...
;         if (old + 1u == (gen + 1u) * nloc) {
;             __builtin_amdgcn_fence(__ATOMIC_RELEASE, "agent");
;             asm volatile("s_waitcnt vmcnt(0)" ::: "memory");
;             const unsigned og = xb_add(&bar[XB_TOP], 1u);
;             const unsigned tg = og / nx;
;             if (og + 1u == (tg + 1u) * nx) xb_add(&bar[XB_TOPGEN], 1u);
;             else XB_SPIN(xb_ld(&bar[XB_TOPGEN]) == tg, bar);
;             __builtin_amdgcn_fence(__ATOMIC_ACQUIRE, "agent");
.LBB0_961:
	s_or_b64 exec, exec, s[10:11]
	v_cvt_f32_u32_e32 v3, v0
	s_waitcnt vmcnt(0)
	v_readfirstlane_b32 s3, v2
	s_add_u32 s10, s62, 0xc3500
	s_addc_u32 s11, s63, 0
	v_rcp_iflag_f32_e32 v3, v3
	v_add_u32_e32 v1, s3, v1
	v_add_u32_e32 v4, 1, v1
	s_mov_b64 s[12:13], -1
	v_mul_f32_e32 v2, 0x4f7ffffe, v3
	v_cvt_u32_f32_e32 v2, v2
	v_sub_u32_e32 v3, 0, v0
	v_mul_lo_u32 v3, v3, v2
	v_mul_hi_u32 v3, v2, v3
	v_add_u32_e32 v2, v2, v3
	v_mul_hi_u32 v2, v1, v2
	v_mul_lo_u32 v3, v2, v0
	v_sub_u32_e32 v1, v1, v3
	v_add_u32_e32 v5, 1, v2
	v_cmp_ge_u32_e32 vcc, v1, v0
	v_sub_u32_e32 v3, v1, v0
	s_nop 0
	v_cndmask_b32_e32 v2, v2, v5, vcc
	v_cndmask_b32_e32 v1, v1, v3, vcc
	v_add_u32_e32 v3, 1, v2
	v_cmp_ge_u32_e32 vcc, v1, v0
	s_nop 1
	v_cndmask_b32_e32 v2, v2, v3, vcc
	v_mul_lo_u32 v1, v0, v2
	v_add_u32_e32 v0, v1, v0
	v_mov_b32_e32 v5, v0
	v_cmp_ne_u32_e32 vcc, v4, v0
	v_mov_b64_e32 v[0:1], s[10:11]
	s_and_saveexec_b64 s[8:9], vcc
	s_cbranch_execz .LBB0_973
	v_mov_b32_e32 v0, 0
	global_load_dword v1, v0, s[10:11] offset:-256 sc1
	s_mov_b64 s[16:17], 0
	s_waitcnt vmcnt(0)
	v_cmp_lt_u32_e32 vcc, v1, v5
	s_and_saveexec_b64 s[14:15], vcc
	s_cbranch_execz .LBB0_972
	s_add_u32 s12, s62, 0xc0200
	s_addc_u32 s13, s63, 0
	s_mov_b32 s3, 1
	s_branch .LBB0_965

; __device__ __forceinline__ unsigned xb_ld(unsigned* p)              { return __hip_atomic_load(p, __ATOMIC_RELAXED, __HIP_MEMORY_SCOPE_AGENT); }
; #define XB_SPIN(cond, bar) do { unsigned _sp = 0; while (cond) { __builtin_amdgcn_s_sleep(1); \
;     if ((++_sp & 255u) == 0u) { if (xb_ld(&(bar)[XB_TMO])) break; if (_sp > XB_SPIN_CAP) { atomicAdd(&(bar)[XB_TMO], 1u); break; } } } } while (0)
; __device__ __forceinline__ void xcd_barrier(const XcdBarrier& b) {
;     ...
;             else XB_SPIN(xb_ld(&bar[XB_TOPGEN]) == tg, bar);
.LBB0_967:
	global_load_dword v1, v0, s[10:11] offset:-256 sc1
	s_add_i32 s3, s3, 1
	s_mov_b64 s[20:21], -1
	s_waitcnt vmcnt(0)
	v_cmp_ge_u32_e32 vcc, v1, v5
	s_orn2_b64 s[24:25], vcc, exec
	s_branch .LBB0_964
